# W_eff on the f32 matrix cores (v_mfma_f32_32x32x2_f32, f32 in/f32 acc) instead of f32 VALU fma chains; all operand loads issued up front
# speedup vs baseline: 1.0010x; 1.0010x over previous
; DEVI unsigned cvtpk(float lo, float hi) { f32x2_t v = {lo, hi}; bf16x2_t b = __builtin_convertvector(v, bf16x2_t); return __builtin_bit_cast(unsigned, b); }
; DEVI const float* IN(int i) { return *(const float* const __attribute__((address_space(4)))*)(kargs() + 8 * i); }
; DEVI void prologue(int wv, LAS unsigned char* lds) {
;     ...
;         const float* wpool = IN(14); const float* pscale = IN(15); const float* wpo = IN(16);
;         for (size_t it = gt; it < (size_t)2 * 65536; it += NGT) {
;             const int l = (int)(it >> 16), r = (int)(it & 65535), kc = r >> 10, n = r & 1023, g = kc >> 4, c0 = (kc & 15) * 8;
;             const float* wp = wpool + (size_t)l * 4 * 128 * 128 + ((size_t)g * 128 + c0) * 128;
;             const float* ps = pscale + l * 512 + g * 128;
;             const float* wo = wpo + (size_t)l * 512 * 1024 + (size_t)g * 128 * 1024 + n;
;             float a0 = 0.f, a1 = 0.f, a2 = 0.f, a3 = 0.f, a4 = 0.f, a5 = 0.f, a6 = 0.f, a7 = 0.f;
; #pragma unroll 16
;             for (int e = 0; e < 128; ++e) { const float x = wo[(size_t)e * 1024] * ps[e];
;                 a0 += wp[e] * x; a1 += wp[128 + e] * x; a2 += wp[256 + e] * x; a3 += wp[384 + e] * x; a4 += wp[512 + e] * x; a5 += wp[640 + e] * x; a6 += wp[768 + e] * x; a7 += wp[896 + e] * x; }
;             u32x4 o; o.x = cvtpk(a0, a1); o.y = cvtpk(a2, a3); o.z = cvtpk(a4, a5); o.w = cvtpk(a6, a7);
;             *(u32x4*)((bf16_t*)(ws + O_W + (size_t)l * W_LAYER + W_EFF) + (size_t)n * 512 + g * 128 + c0) = o;
;         }
.Lpro_b:
	s_mov_b64 s[8:9], 0x20000
	s_mov_b64 s[2:3], s[0:1]
	s_mov_b64 s[24:25], s[0:1]
	s_mov_b64 s[26:27], s[0:1]
	v_cmp_gt_u64_e32 vcc, s[8:9], v[68:69]
	s_and_saveexec_b64 s[8:9], vcc
	s_cbranch_execz .LBB0_336
	s_bitcmp1_b32 s33, 0
	s_cbranch_scc1 .LBB0_336
	s_load_dwordx2 s[28:29], s[0:1], 0x80
	s_load_dwordx2 s[10:11], s[0:1], 0x70
	s_load_dwordx2 s[12:13], s[0:1], 0x78
	s_lshl_b32 s15, s18, 2
	s_lshr_b32 s2, s33, 1
	s_add_i32 s15, s15, s2
	s_lshl_b32 s5, s16, 2
	v_and_b32_e32 v52, 31, v64
	v_bfe_u32 v53, v64, 5, 1
	v_lshlrev_b32_e32 v54, 9, v52
	v_lshl_or_b32 v54, v53, 8, v54
	v_lshlrev_b32_e32 v55, 8, v53
	v_lshlrev_b32_e32 v56, 18, v53
	v_lshl_or_b32 v56, v52, 2, v56
	v_lshlrev_b32_e32 v57, 10, v52
	v_lshl_or_b32 v57, v53, 3, v57
	s_waitcnt lgkmcnt(0)
.Lwm_outer:
	s_cmp_ge_u32 s15, 0x400
	s_cbranch_scc1 .LBB0_336
	s_lshr_b32 s2, s15, 7
	s_and_b32 s3, s15, 3
	s_bfe_u32 s24, s15, 0x50002
	s_lshl_b32 s25, s2, 16
	s_lshl_b32 s26, s3, 14
	s_add_i32 s25, s25, s26
	s_add_u32 s26, s10, s25
	s_addc_u32 s27, s11, 0
	global_load_dwordx4 v[70:73], v54, s[26:27]
	global_load_dwordx4 v[74:77], v54, s[26:27] offset:16
	global_load_dwordx4 v[78:81], v54, s[26:27] offset:32
	global_load_dwordx4 v[82:85], v54, s[26:27] offset:48
	global_load_dwordx4 v[86:89], v54, s[26:27] offset:64
	global_load_dwordx4 v[90:93], v54, s[26:27] offset:80
	global_load_dwordx4 v[94:97], v54, s[26:27] offset:96
	global_load_dwordx4 v[98:101], v54, s[26:27] offset:112
	global_load_dwordx4 v[102:105], v54, s[26:27] offset:128
	global_load_dwordx4 v[106:109], v54, s[26:27] offset:144
	global_load_dwordx4 v[110:113], v54, s[26:27] offset:160
	global_load_dwordx4 v[114:117], v54, s[26:27] offset:176
	global_load_dwordx4 v[118:121], v54, s[26:27] offset:192
	global_load_dwordx4 v[122:125], v54, s[26:27] offset:208
	global_load_dwordx4 v[126:129], v54, s[26:27] offset:224
	global_load_dwordx4 v[130:133], v54, s[26:27] offset:240
	s_lshl_b32 s25, s2, 9
	s_add_u32 s30, s12, s25
	s_addc_u32 s31, s13, 0
	global_load_dwordx4 v[198:201], v55, s[30:31]
	global_load_dwordx4 v[202:205], v55, s[30:31] offset:16
	global_load_dwordx4 v[206:209], v55, s[30:31] offset:32
	global_load_dwordx4 v[210:213], v55, s[30:31] offset:48
	global_load_dwordx4 v[214:217], v55, s[30:31] offset:64
	global_load_dwordx4 v[218:221], v55, s[30:31] offset:80
	global_load_dwordx4 v[222:225], v55, s[30:31] offset:96
	global_load_dwordx4 v[226:229], v55, s[30:31] offset:112
	global_load_dwordx4 v[0:3], v55, s[30:31] offset:128
	global_load_dwordx4 v[4:7], v55, s[30:31] offset:144
	global_load_dwordx4 v[8:11], v55, s[30:31] offset:160
	global_load_dwordx4 v[12:15], v55, s[30:31] offset:176
	global_load_dwordx4 v[16:19], v55, s[30:31] offset:192
	global_load_dwordx4 v[20:23], v55, s[30:31] offset:208
	global_load_dwordx4 v[24:27], v55, s[30:31] offset:224
	global_load_dwordx4 v[28:31], v55, s[30:31] offset:240
	s_lshl_b32 s25, s2, 19
	s_lshl_b32 s34, s24, 7
	s_add_i32 s25, s25, s34
	s_add_u32 s34, s28, s25
	s_addc_u32 s35, s29, 0
	global_load_dword v134, v56, s[34:35]
	s_add_u32 s34, s34, 0x1000
	s_addc_u32 s35, s35, 0
	global_load_dword v135, v56, s[34:35]
	s_add_u32 s34, s34, 0x1000
	s_addc_u32 s35, s35, 0
	global_load_dword v136, v56, s[34:35]
	s_add_u32 s34, s34, 0x1000
	s_addc_u32 s35, s35, 0
	global_load_dword v137, v56, s[34:35]
	s_add_u32 s34, s34, 0x1000
	s_addc_u32 s35, s35, 0
	global_load_dword v138, v56, s[34:35]
	s_add_u32 s34, s34, 0x1000
	s_addc_u32 s35, s35, 0
	global_load_dword v139, v56, s[34:35]
	s_add_u32 s34, s34, 0x1000
	s_addc_u32 s35, s35, 0
	global_load_dword v140, v56, s[34:35]
	s_add_u32 s34, s34, 0x1000
	s_addc_u32 s35, s35, 0
	global_load_dword v141, v56, s[34:35]
	s_add_u32 s34, s34, 0x1000
	s_addc_u32 s35, s35, 0
	global_load_dword v142, v56, s[34:35]
	s_add_u32 s34, s34, 0x1000
	s_addc_u32 s35, s35, 0
	global_load_dword v143, v56, s[34:35]
	s_add_u32 s34, s34, 0x1000
	s_addc_u32 s35, s35, 0
	global_load_dword v144, v56, s[34:35]
	s_add_u32 s34, s34, 0x1000
	s_addc_u32 s35, s35, 0
	global_load_dword v145, v56, s[34:35]
	s_add_u32 s34, s34, 0x1000
	s_addc_u32 s35, s35, 0
	global_load_dword v146, v56, s[34:35]
	s_add_u32 s34, s34, 0x1000
	s_addc_u32 s35, s35, 0
	global_load_dword v147, v56, s[34:35]
	s_add_u32 s34, s34, 0x1000
	s_addc_u32 s35, s35, 0
	global_load_dword v148, v56, s[34:35]
	s_add_u32 s34, s34, 0x1000
	s_addc_u32 s35, s35, 0
	global_load_dword v149, v56, s[34:35]
	s_add_u32 s34, s34, 0x1000
	s_addc_u32 s35, s35, 0
	global_load_dword v150, v56, s[34:35]
	s_add_u32 s34, s34, 0x1000
	s_addc_u32 s35, s35, 0
	global_load_dword v151, v56, s[34:35]
	s_add_u32 s34, s34, 0x1000
	s_addc_u32 s35, s35, 0
	global_load_dword v152, v56, s[34:35]
	s_add_u32 s34, s34, 0x1000
	s_addc_u32 s35, s35, 0
	global_load_dword v153, v56, s[34:35]
	s_add_u32 s34, s34, 0x1000
	s_addc_u32 s35, s35, 0
	global_load_dword v154, v56, s[34:35]
	s_add_u32 s34, s34, 0x1000
	s_addc_u32 s35, s35, 0
	global_load_dword v155, v56, s[34:35]
	s_add_u32 s34, s34, 0x1000
	s_addc_u32 s35, s35, 0
	global_load_dword v156, v56, s[34:35]
	s_add_u32 s34, s34, 0x1000
	s_addc_u32 s35, s35, 0
	global_load_dword v157, v56, s[34:35]
	s_add_u32 s34, s34, 0x1000
	s_addc_u32 s35, s35, 0
	global_load_dword v158, v56, s[34:35]
	s_add_u32 s34, s34, 0x1000
	s_addc_u32 s35, s35, 0
	global_load_dword v159, v56, s[34:35]
	s_add_u32 s34, s34, 0x1000
	s_addc_u32 s35, s35, 0
	global_load_dword v160, v56, s[34:35]
	s_add_u32 s34, s34, 0x1000
	s_addc_u32 s35, s35, 0
	global_load_dword v161, v56, s[34:35]
	s_add_u32 s34, s34, 0x1000
	s_addc_u32 s35, s35, 0
	global_load_dword v162, v56, s[34:35]
	s_add_u32 s34, s34, 0x1000
; DEVI unsigned cvtpk(float lo, float hi) { f32x2_t v = {lo, hi}; bf16x2_t b = __builtin_convertvector(v, bf16x2_t); return __builtin_bit_cast(unsigned, b); }
; DEVI const float* IN(int i) { return *(const float* const __attribute__((address_space(4)))*)(kargs() + 8 * i); }
; DEVI void prologue(int wv, LAS unsigned char* lds) {
;     ...
;         const float* wpool = IN(14); const float* pscale = IN(15); const float* wpo = IN(16);
;         for (size_t it = gt; it < (size_t)2 * 65536; it += NGT) {
;             const int l = (int)(it >> 16), r = (int)(it & 65535), kc = r >> 10, n = r & 1023, g = kc >> 4, c0 = (kc & 15) * 8;
;             const float* wp = wpool + (size_t)l * 4 * 128 * 128 + ((size_t)g * 128 + c0) * 128;
;             const float* ps = pscale + l * 512 + g * 128;
;             const float* wo = wpo + (size_t)l * 512 * 1024 + (size_t)g * 128 * 1024 + n;
;             float a0 = 0.f, a1 = 0.f, a2 = 0.f, a3 = 0.f, a4 = 0.f, a5 = 0.f, a6 = 0.f, a7 = 0.f;
; #pragma unroll 16
;             for (int e = 0; e < 128; ++e) { const float x = wo[(size_t)e * 1024] * ps[e];
;                 a0 += wp[e] * x; a1 += wp[128 + e] * x; a2 += wp[256 + e] * x; a3 += wp[384 + e] * x; a4 += wp[512 + e] * x; a5 += wp[640 + e] * x; a6 += wp[768 + e] * x; a7 += wp[896 + e] * x; }
;             u32x4 o; o.x = cvtpk(a0, a1); o.y = cvtpk(a2, a3); o.z = cvtpk(a4, a5); o.w = cvtpk(a6, a7);
;             *(u32x4*)((bf16_t*)(ws + O_W + (size_t)l * W_LAYER + W_EFF) + (size_t)n * 512 + g * 128 + c0) = o;
;         }
	s_addc_u32 s35, s35, 0
	global_load_dword v163, v56, s[34:35]
	s_add_u32 s34, s34, 0x1000
	s_addc_u32 s35, s35, 0
	global_load_dword v164, v56, s[34:35]
	s_add_u32 s34, s34, 0x1000
	s_addc_u32 s35, s35, 0
	global_load_dword v165, v56, s[34:35]
	s_add_u32 s34, s34, 0x1000
	s_addc_u32 s35, s35, 0
	global_load_dword v166, v56, s[34:35]
	s_add_u32 s34, s34, 0x1000
	s_addc_u32 s35, s35, 0
	global_load_dword v167, v56, s[34:35]
	s_add_u32 s34, s34, 0x1000
	s_addc_u32 s35, s35, 0
	global_load_dword v168, v56, s[34:35]
	s_add_u32 s34, s34, 0x1000
	s_addc_u32 s35, s35, 0
	global_load_dword v169, v56, s[34:35]
	s_add_u32 s34, s34, 0x1000
	s_addc_u32 s35, s35, 0
	global_load_dword v170, v56, s[34:35]
	s_add_u32 s34, s34, 0x1000
	s_addc_u32 s35, s35, 0
	global_load_dword v171, v56, s[34:35]
	s_add_u32 s34, s34, 0x1000
	s_addc_u32 s35, s35, 0
	global_load_dword v172, v56, s[34:35]
	s_add_u32 s34, s34, 0x1000
	s_addc_u32 s35, s35, 0
	global_load_dword v173, v56, s[34:35]
	s_add_u32 s34, s34, 0x1000
	s_addc_u32 s35, s35, 0
	global_load_dword v174, v56, s[34:35]
	s_add_u32 s34, s34, 0x1000
	s_addc_u32 s35, s35, 0
	global_load_dword v175, v56, s[34:35]
	s_add_u32 s34, s34, 0x1000
	s_addc_u32 s35, s35, 0
	global_load_dword v176, v56, s[34:35]
	s_add_u32 s34, s34, 0x1000
	s_addc_u32 s35, s35, 0
	global_load_dword v177, v56, s[34:35]
	s_add_u32 s34, s34, 0x1000
	s_addc_u32 s35, s35, 0
	global_load_dword v178, v56, s[34:35]
	s_add_u32 s34, s34, 0x1000
	s_addc_u32 s35, s35, 0
	global_load_dword v179, v56, s[34:35]
	s_add_u32 s34, s34, 0x1000
	s_addc_u32 s35, s35, 0
	global_load_dword v180, v56, s[34:35]
	s_add_u32 s34, s34, 0x1000
	s_addc_u32 s35, s35, 0
	global_load_dword v181, v56, s[34:35]
	s_add_u32 s34, s34, 0x1000
	s_addc_u32 s35, s35, 0
	global_load_dword v182, v56, s[34:35]
	s_add_u32 s34, s34, 0x1000
	s_addc_u32 s35, s35, 0
	global_load_dword v183, v56, s[34:35]
	s_add_u32 s34, s34, 0x1000
	s_addc_u32 s35, s35, 0
	global_load_dword v184, v56, s[34:35]
	s_add_u32 s34, s34, 0x1000
	s_addc_u32 s35, s35, 0
	global_load_dword v185, v56, s[34:35]
	s_add_u32 s34, s34, 0x1000
	s_addc_u32 s35, s35, 0
	global_load_dword v186, v56, s[34:35]
	s_add_u32 s34, s34, 0x1000
	s_addc_u32 s35, s35, 0
	global_load_dword v187, v56, s[34:35]
	s_add_u32 s34, s34, 0x1000
	s_addc_u32 s35, s35, 0
	global_load_dword v188, v56, s[34:35]
	s_add_u32 s34, s34, 0x1000
	s_addc_u32 s35, s35, 0
	global_load_dword v189, v56, s[34:35]
	s_add_u32 s34, s34, 0x1000
	s_addc_u32 s35, s35, 0
	global_load_dword v190, v56, s[34:35]
	s_add_u32 s34, s34, 0x1000
	s_addc_u32 s35, s35, 0
	global_load_dword v191, v56, s[34:35]
	s_add_u32 s34, s34, 0x1000
	s_addc_u32 s35, s35, 0
	global_load_dword v192, v56, s[34:35]
	s_add_u32 s34, s34, 0x1000
	s_addc_u32 s35, s35, 0
	global_load_dword v193, v56, s[34:35]
	s_add_u32 s34, s34, 0x1000
	s_addc_u32 s35, s35, 0
	global_load_dword v194, v56, s[34:35]
	s_add_u32 s34, s34, 0x1000
	s_addc_u32 s35, s35, 0
	global_load_dword v195, v56, s[34:35]
	s_add_u32 s34, s34, 0x1000
	s_addc_u32 s35, s35, 0
	global_load_dword v196, v56, s[34:35]
	s_add_u32 s34, s34, 0x1000
	s_addc_u32 s35, s35, 0
	global_load_dword v197, v56, s[34:35]
	v_mov_b32_e32 v36, 0
	v_mov_b32_e32 v37, 0
	v_mov_b32_e32 v38, 0
	v_mov_b32_e32 v39, 0
	v_mov_b32_e32 v40, 0
	v_mov_b32_e32 v41, 0
	v_mov_b32_e32 v42, 0
	v_mov_b32_e32 v43, 0
	v_mov_b32_e32 v44, 0
	v_mov_b32_e32 v45, 0
	v_mov_b32_e32 v46, 0
	v_mov_b32_e32 v47, 0
	v_mov_b32_e32 v48, 0
	v_mov_b32_e32 v49, 0
	v_mov_b32_e32 v50, 0
	v_mov_b32_e32 v51, 0
	s_waitcnt vmcnt(63)
	v_mul_f32_e32 v134, v134, v198
	s_waitcnt vmcnt(62)
	v_mul_f32_e32 v135, v135, v199
	v_mfma_f32_32x32x2_f32 v[36:51], v70, v134, v[36:51]
	s_waitcnt vmcnt(61)
	v_mul_f32_e32 v136, v136, v200
	v_mfma_f32_32x32x2_f32 v[36:51], v71, v135, v[36:51]
	s_waitcnt vmcnt(60)
	v_mul_f32_e32 v137, v137, v201
	v_mfma_f32_32x32x2_f32 v[36:51], v72, v136, v[36:51]
	s_waitcnt vmcnt(59)
	v_mul_f32_e32 v138, v138, v202
	v_mfma_f32_32x32x2_f32 v[36:51], v73, v137, v[36:51]
	s_waitcnt vmcnt(58)
	v_mul_f32_e32 v139, v139, v203
	v_mfma_f32_32x32x2_f32 v[36:51], v74, v138, v[36:51]
	s_waitcnt vmcnt(57)
	v_mul_f32_e32 v140, v140, v204
	v_mfma_f32_32x32x2_f32 v[36:51], v75, v139, v[36:51]
	s_waitcnt vmcnt(56)
	v_mul_f32_e32 v141, v141, v205
	v_mfma_f32_32x32x2_f32 v[36:51], v76, v140, v[36:51]
	s_waitcnt vmcnt(55)
	v_mul_f32_e32 v142, v142, v206
	v_mfma_f32_32x32x2_f32 v[36:51], v77, v141, v[36:51]
	s_waitcnt vmcnt(54)
	v_mul_f32_e32 v143, v143, v207
	v_mfma_f32_32x32x2_f32 v[36:51], v78, v142, v[36:51]
	s_waitcnt vmcnt(53)
	v_mul_f32_e32 v144, v144, v208
	v_mfma_f32_32x32x2_f32 v[36:51], v79, v143, v[36:51]
	s_waitcnt vmcnt(52)
	v_mul_f32_e32 v145, v145, v209
	v_mfma_f32_32x32x2_f32 v[36:51], v80, v144, v[36:51]
	s_waitcnt vmcnt(51)
	v_mul_f32_e32 v146, v146, v210
	v_mfma_f32_32x32x2_f32 v[36:51], v81, v145, v[36:51]
	s_waitcnt vmcnt(50)
	v_mul_f32_e32 v147, v147, v211
	v_mfma_f32_32x32x2_f32 v[36:51], v82, v146, v[36:51]
	s_waitcnt vmcnt(49)
	v_mul_f32_e32 v148, v148, v212
	v_mfma_f32_32x32x2_f32 v[36:51], v83, v147, v[36:51]
	s_waitcnt vmcnt(48)
	v_mul_f32_e32 v149, v149, v213
	v_mfma_f32_32x32x2_f32 v[36:51], v84, v148, v[36:51]
	s_waitcnt vmcnt(47)
	v_mul_f32_e32 v150, v150, v214
	v_mfma_f32_32x32x2_f32 v[36:51], v85, v149, v[36:51]
	s_waitcnt vmcnt(46)
	v_mul_f32_e32 v151, v151, v215
	v_mfma_f32_32x32x2_f32 v[36:51], v86, v150, v[36:51]
	s_waitcnt vmcnt(45)
	v_mul_f32_e32 v152, v152, v216
	v_mfma_f32_32x32x2_f32 v[36:51], v87, v151, v[36:51]
	s_waitcnt vmcnt(44)
	v_mul_f32_e32 v153, v153, v217
	v_mfma_f32_32x32x2_f32 v[36:51], v88, v152, v[36:51]
	s_waitcnt vmcnt(43)
; DEVI unsigned cvtpk(float lo, float hi) { f32x2_t v = {lo, hi}; bf16x2_t b = __builtin_convertvector(v, bf16x2_t); return __builtin_bit_cast(unsigned, b); }
; DEVI const float* IN(int i) { return *(const float* const __attribute__((address_space(4)))*)(kargs() + 8 * i); }
; DEVI void prologue(int wv, LAS unsigned char* lds) {
;     ...
;         const float* wpool = IN(14); const float* pscale = IN(15); const float* wpo = IN(16);
;         for (size_t it = gt; it < (size_t)2 * 65536; it += NGT) {
;             const int l = (int)(it >> 16), r = (int)(it & 65535), kc = r >> 10, n = r & 1023, g = kc >> 4, c0 = (kc & 15) * 8;
;             const float* wp = wpool + (size_t)l * 4 * 128 * 128 + ((size_t)g * 128 + c0) * 128;
;             const float* ps = pscale + l * 512 + g * 128;
;             const float* wo = wpo + (size_t)l * 512 * 1024 + (size_t)g * 128 * 1024 + n;
;             float a0 = 0.f, a1 = 0.f, a2 = 0.f, a3 = 0.f, a4 = 0.f, a5 = 0.f, a6 = 0.f, a7 = 0.f;
; #pragma unroll 16
;             for (int e = 0; e < 128; ++e) { const float x = wo[(size_t)e * 1024] * ps[e];
;                 a0 += wp[e] * x; a1 += wp[128 + e] * x; a2 += wp[256 + e] * x; a3 += wp[384 + e] * x; a4 += wp[512 + e] * x; a5 += wp[640 + e] * x; a6 += wp[768 + e] * x; a7 += wp[896 + e] * x; }
;             u32x4 o; o.x = cvtpk(a0, a1); o.y = cvtpk(a2, a3); o.z = cvtpk(a4, a5); o.w = cvtpk(a6, a7);
;             *(u32x4*)((bf16_t*)(ws + O_W + (size_t)l * W_LAYER + W_EFF) + (size_t)n * 512 + g * 128 + c0) = o;
;         }
	v_mul_f32_e32 v154, v154, v218
	v_mfma_f32_32x32x2_f32 v[36:51], v89, v153, v[36:51]
	s_waitcnt vmcnt(42)
	v_mul_f32_e32 v155, v155, v219
	v_mfma_f32_32x32x2_f32 v[36:51], v90, v154, v[36:51]
	s_waitcnt vmcnt(41)
	v_mul_f32_e32 v156, v156, v220
	v_mfma_f32_32x32x2_f32 v[36:51], v91, v155, v[36:51]
	s_waitcnt vmcnt(40)
	v_mul_f32_e32 v157, v157, v221
	v_mfma_f32_32x32x2_f32 v[36:51], v92, v156, v[36:51]
	s_waitcnt vmcnt(39)
	v_mul_f32_e32 v158, v158, v222
	v_mfma_f32_32x32x2_f32 v[36:51], v93, v157, v[36:51]
	s_waitcnt vmcnt(38)
	v_mul_f32_e32 v159, v159, v223
	v_mfma_f32_32x32x2_f32 v[36:51], v94, v158, v[36:51]
	s_waitcnt vmcnt(37)
	v_mul_f32_e32 v160, v160, v224
	v_mfma_f32_32x32x2_f32 v[36:51], v95, v159, v[36:51]
	s_waitcnt vmcnt(36)
	v_mul_f32_e32 v161, v161, v225
	v_mfma_f32_32x32x2_f32 v[36:51], v96, v160, v[36:51]
	s_waitcnt vmcnt(35)
	v_mul_f32_e32 v162, v162, v226
	v_mfma_f32_32x32x2_f32 v[36:51], v97, v161, v[36:51]
	s_waitcnt vmcnt(34)
	v_mul_f32_e32 v163, v163, v227
	v_mfma_f32_32x32x2_f32 v[36:51], v98, v162, v[36:51]
	s_waitcnt vmcnt(33)
	v_mul_f32_e32 v164, v164, v228
	v_mfma_f32_32x32x2_f32 v[36:51], v99, v163, v[36:51]
	s_waitcnt vmcnt(32)
	v_mul_f32_e32 v165, v165, v229
	v_mfma_f32_32x32x2_f32 v[36:51], v100, v164, v[36:51]
	s_waitcnt vmcnt(31)
	v_mul_f32_e32 v166, v166, v0
	v_mfma_f32_32x32x2_f32 v[36:51], v101, v165, v[36:51]
	s_waitcnt vmcnt(30)
	v_mul_f32_e32 v167, v167, v1
	v_mfma_f32_32x32x2_f32 v[36:51], v102, v166, v[36:51]
	s_waitcnt vmcnt(29)
	v_mul_f32_e32 v168, v168, v2
	v_mfma_f32_32x32x2_f32 v[36:51], v103, v167, v[36:51]
	s_waitcnt vmcnt(28)
	v_mul_f32_e32 v169, v169, v3
	v_mfma_f32_32x32x2_f32 v[36:51], v104, v168, v[36:51]
	s_waitcnt vmcnt(27)
	v_mul_f32_e32 v170, v170, v4
	v_mfma_f32_32x32x2_f32 v[36:51], v105, v169, v[36:51]
	s_waitcnt vmcnt(26)
	v_mul_f32_e32 v171, v171, v5
	v_mfma_f32_32x32x2_f32 v[36:51], v106, v170, v[36:51]
	s_waitcnt vmcnt(25)
	v_mul_f32_e32 v172, v172, v6
	v_mfma_f32_32x32x2_f32 v[36:51], v107, v171, v[36:51]
	s_waitcnt vmcnt(24)
	v_mul_f32_e32 v173, v173, v7
	v_mfma_f32_32x32x2_f32 v[36:51], v108, v172, v[36:51]
	s_waitcnt vmcnt(23)
	v_mul_f32_e32 v174, v174, v8
	v_mfma_f32_32x32x2_f32 v[36:51], v109, v173, v[36:51]
	s_waitcnt vmcnt(22)
	v_mul_f32_e32 v175, v175, v9
	v_mfma_f32_32x32x2_f32 v[36:51], v110, v174, v[36:51]
	s_waitcnt vmcnt(21)
	v_mul_f32_e32 v176, v176, v10
	v_mfma_f32_32x32x2_f32 v[36:51], v111, v175, v[36:51]
	s_waitcnt vmcnt(20)
	v_mul_f32_e32 v177, v177, v11
	v_mfma_f32_32x32x2_f32 v[36:51], v112, v176, v[36:51]
	s_waitcnt vmcnt(19)
	v_mul_f32_e32 v178, v178, v12
	v_mfma_f32_32x32x2_f32 v[36:51], v113, v177, v[36:51]
	s_waitcnt vmcnt(18)
	v_mul_f32_e32 v179, v179, v13
	v_mfma_f32_32x32x2_f32 v[36:51], v114, v178, v[36:51]
	s_waitcnt vmcnt(17)
	v_mul_f32_e32 v180, v180, v14
	v_mfma_f32_32x32x2_f32 v[36:51], v115, v179, v[36:51]
	s_waitcnt vmcnt(16)
	v_mul_f32_e32 v181, v181, v15
	v_mfma_f32_32x32x2_f32 v[36:51], v116, v180, v[36:51]
	s_waitcnt vmcnt(15)
	v_mul_f32_e32 v182, v182, v16
	v_mfma_f32_32x32x2_f32 v[36:51], v117, v181, v[36:51]
	s_waitcnt vmcnt(14)
	v_mul_f32_e32 v183, v183, v17
	v_mfma_f32_32x32x2_f32 v[36:51], v118, v182, v[36:51]
	s_waitcnt vmcnt(13)
	v_mul_f32_e32 v184, v184, v18
	v_mfma_f32_32x32x2_f32 v[36:51], v119, v183, v[36:51]
	s_waitcnt vmcnt(12)
	v_mul_f32_e32 v185, v185, v19
	v_mfma_f32_32x32x2_f32 v[36:51], v120, v184, v[36:51]
	s_waitcnt vmcnt(11)
	v_mul_f32_e32 v186, v186, v20
	v_mfma_f32_32x32x2_f32 v[36:51], v121, v185, v[36:51]
	s_waitcnt vmcnt(10)
	v_mul_f32_e32 v187, v187, v21
	v_mfma_f32_32x32x2_f32 v[36:51], v122, v186, v[36:51]
	s_waitcnt vmcnt(9)
	v_mul_f32_e32 v188, v188, v22
	v_mfma_f32_32x32x2_f32 v[36:51], v123, v187, v[36:51]
	s_waitcnt vmcnt(8)
	v_mul_f32_e32 v189, v189, v23
	v_mfma_f32_32x32x2_f32 v[36:51], v124, v188, v[36:51]
	s_waitcnt vmcnt(7)
	v_mul_f32_e32 v190, v190, v24
	v_mfma_f32_32x32x2_f32 v[36:51], v125, v189, v[36:51]
	s_waitcnt vmcnt(6)
	v_mul_f32_e32 v191, v191, v25
	v_mfma_f32_32x32x2_f32 v[36:51], v126, v190, v[36:51]
	s_waitcnt vmcnt(5)
	v_mul_f32_e32 v192, v192, v26
	v_mfma_f32_32x32x2_f32 v[36:51], v127, v191, v[36:51]
	s_waitcnt vmcnt(4)
	v_mul_f32_e32 v193, v193, v27
	v_mfma_f32_32x32x2_f32 v[36:51], v128, v192, v[36:51]
	s_waitcnt vmcnt(3)
	v_mul_f32_e32 v194, v194, v28
	v_mfma_f32_32x32x2_f32 v[36:51], v129, v193, v[36:51]
	s_waitcnt vmcnt(2)
	v_mul_f32_e32 v195, v195, v29
	v_mfma_f32_32x32x2_f32 v[36:51], v130, v194, v[36:51]
	s_waitcnt vmcnt(1)
	v_mul_f32_e32 v196, v196, v30
	v_mfma_f32_32x32x2_f32 v[36:51], v131, v195, v[36:51]
	s_waitcnt vmcnt(0)
	v_mul_f32_e32 v197, v197, v31
	v_mfma_f32_32x32x2_f32 v[36:51], v132, v196, v[36:51]
	s_nop 1
	v_mfma_f32_32x32x2_f32 v[36:51], v133, v197, v[36:51]
	s_lshr_b32 s25, s2, 2
	s_mul_i32 s25, s25, 0x1c10000
	s_and_b32 s26, s2, 3
	s_lshl_b32 s26, s26, 8
	s_add_i32 s25, s25, s26
	s_lshl_b32 s26, s3, 6
	s_add_i32 s25, s25, s26
	s_lshl_b32 s26, s24, 15
	s_add_i32 s25, s25, s26
	s_add_i32 s25, s25, 0xca0800
	s_add_u32 s36, s20, s25
	s_addc_u32 s37, s21, 0
	s_nop 7
	s_nop 7
	s_nop 7
	v_cvt_pk_bf16_f32 v58, v36, v37
	v_cvt_pk_bf16_f32 v59, v38, v39
	global_store_dwordx2 v57, v[58:59], s[36:37]
	v_cvt_pk_bf16_f32 v60, v40, v41
	v_cvt_pk_bf16_f32 v61, v42, v43
	global_store_dwordx2 v57, v[60:61], s[36:37] offset:16
	v_cvt_pk_bf16_f32 v58, v44, v45
	v_cvt_pk_bf16_f32 v59, v46, v47
	global_store_dwordx2 v57, v[58:59], s[36:37] offset:32
	v_cvt_pk_bf16_f32 v60, v48, v49
	v_cvt_pk_bf16_f32 v61, v50, v51
	global_store_dwordx2 v57, v[60:61], s[36:37] offset:48
	s_add_i32 s15, s15, s5
	s_branch .Lwm_outer
